# MLA long-unit tile loop rewritten: QK(hf1) overlapped with softmax(hf0), PV overlapped with softmax(hf1), LDS-DMA pieces interleaved among MFMAs
# speedup vs baseline: 1.0036x; 1.0027x over previous
; template <bool DIFF, bool NOMAX>
; DI void unit(LAS unsigned char* lds, const Tensors& Tn, int b, int hd, int qb) {
;     ...
;     for (int j = jbeg; j < ntiles; ++j) {
;         const int sbn = (sb + NSTG - 1 >= NSTG) ? sb - 1 : sb + NSTG - 1;
;         if (j + NSTG - 1 < ntiles) ATT_ISSUE(j + NSTG - 1, sbn);
;         if (j >= jst && j < need) {
.LBB0_1378:
	s_cmp_gt_i32 s84, s47
	s_cbranch_scc0 .LBB0_1389
	s_add_i32 s80, s84, 2
	s_cmp_ge_u32 s80, s29
	s_cbranch_scc1 .LBB0_1386
	s_cmp_gt_i32 s51, 0
	s_cselect_b32 s80, -1, 2
	s_add_i32 s80, s80, s51
	s_mul_i32 s80, s80, 0xb400
	s_and_b64 vcc, exec, s[4:5]
	s_add_i32 s80, s80, 0
	s_cbranch_vccz .LBB0_1395
	s_and_b64 vcc, exec, s[6:7]
	s_cbranch_vccz .LBB0_1396

; template <bool DIFF, bool NOMAX>
; DI void unit(LAS unsigned char* lds, const Tensors& Tn, int b, int hd, int qb) {
;     ...
; #pragma unroll
;                 for (int ks = 0; ks < NKS; ++ks) {
;                     sc = mfma32(kf[ks % DK], qf[ks], sc);
;                     if (ks + DK < NKS) kf[ks % DK] = LDK(hf, ks + DK);
;                 }
; #pragma unroll
;                 for (int ks = 0; ks < NKS; ++ks) { SGB(0x8, 1); if (ks + DK < NKS) SGB(0x100, 1); }
;                 __builtin_amdgcn_sched_barrier(0);
; #pragma unroll
;                 for (int i = 0; i < DV; ++i) LDV(i, hf);
;                 if (DIFF && !offd) {
;                     const float qk = (float)(q0 + r - 64 * j - 4 * h - 32 * hf);
;                     float tq[4] = {qk, qk - 8.f, qk - 16.f, qk - 24.f};
; #pragma unroll
;                     for (int g = 0; g < 4; ++g) asm volatile("" : "+v"(tq[g]));
; #pragma unroll
;                     for (int e = 0; e < 16; ++e) sc[e] = __builtin_fmaf(-sl2, __builtin_fabsf(tq[e >> 2] - (float)(e & 3)), sc[e]);
;                 }
;                 float mx = sc[0];
;                 if (!NOMAX) {
; #pragma unroll
;                 for (int e = 1; e < 16; ++e) mx = __builtin_fmaxf(mx, sc[e]);
;                 { auto rr = __builtin_amdgcn_permlane32_swap(__builtin_bit_cast(unsigned, mx), __builtin_bit_cast(unsigned, mx), false, false);
;                   mx = __builtin_fmaxf(__builtin_bit_cast(float, rr[0]), __builtin_bit_cast(float, rr[1])); }
;                 }
;                 const bool first = (j == jst) && (hf == 0);
;                 if (!NOMAX && (first || __any(mx > 8.0f))) {
;                     const float mn = first ? mx : __builtin_fmaxf(mx, 0.f), al = first ? 1.0f : fast_exp2(-mn);
; #pragma unroll
;                     for (int dt = 0; dt < NDT; ++dt) o[dt] = o[dt] * al;
;                     lrow *= al; mrow += mn;
; #pragma unroll
;                     for (int e = 0; e < 16; ++e) sc[e] -= mn;
;                 }
;                 f32x2_t ps2 = {0.f, 0.f};
; #pragma unroll
;                 for (int e = 0; e < 16; e += 2) { sc[e] = fast_exp2(sc[e]); sc[e + 1] = fast_exp2(sc[e + 1]); ps2 += (f32x2_t){sc[e], sc[e + 1]}; }
;                 lrow += ps2.x + ps2.y;
;                 bf16x8 pb[2]; pb[0] = pack8(sc, 0); pb[1] = pack8(sc, 1);
; #pragma unroll
;                 for (int i = 0; i < NPV; ++i) {
.LBB0_1389:
	s_mul_i32 s80, s51, 0xb400
	s_add_i32 s80, s80, 0
	v_add3_u32 v0, s80, v170, v144
	s_add_i32 s99, s84, 2
	s_cmp_lt_u32 s99, s29
	s_cselect_b32 s99, 1, 0
	s_cmp_gt_i32 s51, 0
	s_cselect_b32 s98, -1, 2
	s_add_i32 s98, s98, s51
	s_mul_i32 s98, s98, 0xb400
	v_mov_b32_e32 v196, 0
	ds_read_b128 v[2:5], v0
	ds_read_b128 v[6:9], v0 offset:32
	ds_read_b128 v[10:13], v0 offset:64
	ds_read_b128 v[174:177], v0 offset:96
	ds_read_b128 v[178:181], v0 offset:128
	ds_read_b128 v[182:185], v0 offset:160
	v_add_u32_e32 v14, s80, v145
	v_add3_u32 v173, v14, v171, s1
	s_waitcnt lgkmcnt(5)
	v_mfma_f32_32x32x16_bf16 v[80:95], v[2:5], v[96:99], 0
	ds_read_b128 v[2:5], v0 offset:192
	s_waitcnt lgkmcnt(5)
	v_mfma_f32_32x32x16_bf16 v[80:95], v[6:9], v[100:103], v[80:95]
	ds_read_b128 v[6:9], v0 offset:224
	s_cmp_lg_u32 s99, 0
	s_cbranch_scc0 .Lpc_skip0_i1
	s_and_b64 vcc, exec, s[4:5]
	s_cbranch_vccnz .Lpc_skip0_i1
	v_lshl_add_u64 v[244:245], s[36:37], 0, v[146:147]
	v_lshl_add_u64 v[246:247], s[36:37], 0, v[158:159]
	v_cndmask_b32_e64 v245, v247, v245, s[14:15]
	v_cndmask_b32_e64 v244, v246, v244, s[14:15]
	s_add_i32 m0, s98, s41
	s_nop 0
	global_load_lds_dwordx4 v[244:245], off
.Lpc_skip0_i1:
	s_waitcnt lgkmcnt(5)
	v_mfma_f32_32x32x16_bf16 v[80:95], v[10:13], v[104:107], v[80:95]
	ds_read_b128 v[10:13], v0 offset:256
	s_waitcnt lgkmcnt(5)
	v_mfma_f32_32x32x16_bf16 v[80:95], v[174:177], v[108:111], v[80:95]
	ds_read_b128 v[174:177], v0 offset:288
	s_waitcnt lgkmcnt(5)
	v_mfma_f32_32x32x16_bf16 v[80:95], v[178:181], v[112:115], v[80:95]
	ds_read_b128 v[178:181], v0 offset:320
	s_cmp_lg_u32 s99, 0
	s_cbranch_scc0 .Lpc_skip1_i1
	s_and_b64 vcc, exec, s[6:7]
	s_cbranch_vccnz .Lpc_skip1_i1
	v_lshl_add_u64 v[244:245], s[36:37], 0, v[148:149]
	v_lshl_add_u64 v[246:247], s[36:37], 0, v[160:161]
	v_cndmask_b32_e64 v245, v247, v245, s[16:17]
	v_cndmask_b32_e64 v244, v246, v244, s[16:17]
	s_add_i32 m0, s98, s56
	s_nop 0
	global_load_lds_dwordx4 v[244:245], off
.Lpc_skip1_i1:
	s_waitcnt lgkmcnt(5)
	v_mfma_f32_32x32x16_bf16 v[80:95], v[182:185], v[116:119], v[80:95]
	ds_read_b128 v[182:185], v0 offset:352
	s_waitcnt lgkmcnt(5)
	v_mfma_f32_32x32x16_bf16 v[80:95], v[2:5], v[120:123], v[80:95]
	ds_read_b128 v[2:5], v0 offset:12800
	s_waitcnt lgkmcnt(5)
	v_mfma_f32_32x32x16_bf16 v[80:95], v[6:9], v[124:127], v[80:95]
	ds_read_b128 v[6:9], v0 offset:12832
	s_cmp_lg_u32 s99, 0
	s_cbranch_scc0 .Lpc_skip2_i1
	s_and_b64 vcc, exec, s[8:9]
	s_cbranch_vccnz .Lpc_skip2_i1
	v_lshl_add_u64 v[244:245], s[36:37], 0, v[150:151]
	v_lshl_add_u64 v[246:247], s[36:37], 0, v[162:163]
	v_cndmask_b32_e64 v245, v247, v245, s[18:19]
	v_cndmask_b32_e64 v244, v246, v244, s[18:19]
	s_add_i32 m0, s98, s57
	s_nop 0
	global_load_lds_dwordx4 v[244:245], off
.Lpc_skip2_i1:
	s_waitcnt lgkmcnt(5)
	v_mfma_f32_32x32x16_bf16 v[80:95], v[10:13], v[128:131], v[80:95]
	ds_read_b128 v[10:13], v0 offset:12864
	s_waitcnt lgkmcnt(5)
	v_mfma_f32_32x32x16_bf16 v[80:95], v[174:177], v[132:135], v[80:95]
	ds_read_b128 v[174:177], v0 offset:12896
	s_waitcnt lgkmcnt(5)
	v_mfma_f32_32x32x16_bf16 v[80:95], v[178:181], v[136:139], v[80:95]
	ds_read_b128 v[178:181], v0 offset:12928
	s_cmp_lg_u32 s99, 0
	s_cbranch_scc0 .Lpc_skip3_i1
	s_and_b64 vcc, exec, s[10:11]
	s_cbranch_vccnz .Lpc_skip3_i1
	v_lshl_add_u64 v[244:245], s[36:37], 0, v[152:153]
	v_lshl_add_u64 v[246:247], s[36:37], 0, v[164:165]
	v_cndmask_b32_e64 v245, v247, v245, s[20:21]
	v_cndmask_b32_e64 v244, v246, v244, s[20:21]
	s_add_i32 m0, s98, s82
	s_nop 0
	global_load_lds_dwordx4 v[244:245], off
.Lpc_skip3_i1:
	s_waitcnt lgkmcnt(5)
	v_mfma_f32_32x32x16_bf16 v[80:95], v[182:185], v[140:143], v[80:95]
	ds_read_b128 v[182:185], v0 offset:12960
	s_waitcnt lgkmcnt(5)
	v_mfma_f32_32x32x16_bf16 v[226:241], v[2:5], v[96:99], 0
	ds_read_b128 v[2:5], v0 offset:12992
	s_waitcnt lgkmcnt(5)
	v_mfma_f32_32x32x16_bf16 v[226:241], v[6:9], v[100:103], v[226:241]
	ds_read_b128 v[6:9], v0 offset:13024
	s_waitcnt lgkmcnt(5)
	v_mfma_f32_32x32x16_bf16 v[226:241], v[10:13], v[104:107], v[226:241]
	ds_read_b128 v[10:13], v0 offset:13056
	s_waitcnt lgkmcnt(5)
	v_mfma_f32_32x32x16_bf16 v[226:241], v[174:177], v[108:111], v[226:241]
	ds_read_b128 v[174:177], v0 offset:13088
	v_exp_f32_e32 v80, v80
	v_exp_f32_e32 v81, v81
	v_add_f32_e32 v172, v172, v80
	v_add_f32_e32 v196, v196, v81
	s_waitcnt lgkmcnt(5)
	v_mfma_f32_32x32x16_bf16 v[226:241], v[178:181], v[112:115], v[226:241]
	ds_read_b128 v[178:181], v0 offset:13120
	v_cvt_pk_bf16_f32 v80, v80, v81
	v_exp_f32_e32 v82, v82
	v_exp_f32_e32 v83, v83
	v_add_f32_e32 v172, v172, v82
	s_waitcnt lgkmcnt(5)
	v_mfma_f32_32x32x16_bf16 v[226:241], v[182:185], v[116:119], v[226:241]
	ds_read_b128 v[182:185], v0 offset:13152
	v_add_f32_e32 v196, v196, v83
	v_cvt_pk_bf16_f32 v81, v82, v83
	v_exp_f32_e32 v84, v84
	v_exp_f32_e32 v85, v85
	s_waitcnt lgkmcnt(5)
	v_mfma_f32_32x32x16_bf16 v[226:241], v[2:5], v[120:123], v[226:241]
	ds_read_b64_tr_b16 v[2:3], v173 offset:0
	ds_read_b64_tr_b16 v[4:5], v173 offset:2560
	v_add_f32_e32 v172, v172, v84
	v_add_f32_e32 v196, v196, v85
	v_cvt_pk_bf16_f32 v82, v84, v85
	v_exp_f32_e32 v86, v86
	v_exp_f32_e32 v87, v87
	s_waitcnt lgkmcnt(6)
	v_mfma_f32_32x32x16_bf16 v[226:241], v[6:9], v[124:127], v[226:241]
	ds_read_b64_tr_b16 v[6:7], v173 offset:64
	ds_read_b64_tr_b16 v[8:9], v173 offset:2624
	v_add_f32_e32 v172, v172, v86
	v_add_f32_e32 v196, v196, v87
	v_cvt_pk_bf16_f32 v83, v86, v87
	v_exp_f32_e32 v88, v88
	v_exp_f32_e32 v89, v89
	s_waitcnt lgkmcnt(7)
	v_mfma_f32_32x32x16_bf16 v[226:241], v[10:13], v[128:131], v[226:241]
	ds_read_b64_tr_b16 v[10:11], v173 offset:128
	ds_read_b64_tr_b16 v[12:13], v173 offset:2688
	v_add_f32_e32 v172, v172, v88
	v_add_f32_e32 v196, v196, v89
	v_cvt_pk_bf16_f32 v84, v88, v89
	v_exp_f32_e32 v90, v90
	v_exp_f32_e32 v91, v91
	s_waitcnt lgkmcnt(8)
	v_mfma_f32_32x32x16_bf16 v[226:241], v[174:177], v[132:135], v[226:241]
	ds_read_b64_tr_b16 v[174:175], v173 offset:192
	ds_read_b64_tr_b16 v[176:177], v173 offset:2752
	v_add_f32_e32 v172, v172, v90
	v_add_f32_e32 v196, v196, v91
	v_cvt_pk_bf16_f32 v85, v90, v91
	v_exp_f32_e32 v92, v92
	v_exp_f32_e32 v93, v93
	s_waitcnt lgkmcnt(9)
	v_mfma_f32_32x32x16_bf16 v[226:241], v[178:181], v[136:139], v[226:241]
	ds_read_b64_tr_b16 v[178:179], v173 offset:5120
	ds_read_b64_tr_b16 v[180:181], v173 offset:7680
	v_add_f32_e32 v172, v172, v92
	v_add_f32_e32 v196, v196, v93
	v_cvt_pk_bf16_f32 v86, v92, v93
	v_exp_f32_e32 v94, v94
	s_waitcnt lgkmcnt(10)
	v_mfma_f32_32x32x16_bf16 v[226:241], v[182:185], v[140:143], v[226:241]
	ds_read_b64_tr_b16 v[182:183], v173 offset:5184
	ds_read_b64_tr_b16 v[184:185], v173 offset:7744
	v_exp_f32_e32 v95, v95
	v_add_f32_e32 v172, v172, v94
	v_add_f32_e32 v196, v196, v95
	v_cvt_pk_bf16_f32 v87, v94, v95
	s_waitcnt lgkmcnt(10)
	v_mfma_f32_32x32x16_bf16 v[64:79], v[2:5], v[80:83], v[64:79]
	ds_read_b64_tr_b16 v[2:3], v173 offset:5248
	ds_read_b64_tr_b16 v[4:5], v173 offset:7808
	s_cmp_lg_u32 s99, 0
	s_cbranch_scc0 .Lpc_skip5_i1
; DI float fast_exp2(float x) { return __builtin_amdgcn_exp2f(x); }
; DI f32x16 mfma32(bf16x8 a, bf16x8 b, f32x16 c) { return __builtin_amdgcn_mfma_f32_32x32x16_bf16(a, b, c, 0, 0, 0); }
; #define SGB(mask, n) __builtin_amdgcn_sched_group_barrier(mask, n, 0)
; #define LDV(i_, hf_) do { VTR(vlo[(i_) % DV], (16 * (2 * (hf_) + ((i_) & 1))) * VSTR + 64 * ((i_) >> 1)); VTR(vhi[(i_) % DV], (16 * (2 * (hf_) + ((i_) & 1)) + 8) * VSTR + 64 * ((i_) >> 1)); } while (0)
; #define VWAIT(n_, a_, b_) asm volatile("s_waitcnt lgkmcnt(%c2)" : "+v"(a_), "+v"(b_) : "i"(n_) : "memory")
; template <bool DIFF, bool NOMAX>
; DI void unit(LAS unsigned char* lds, const Tensors& Tn, int b, int hd, int qb) {
;     ...
;                 f32x2_t ps2 = {0.f, 0.f};
; #pragma unroll
;                 for (int e = 0; e < 16; e += 2) { sc[e] = fast_exp2(sc[e]); sc[e + 1] = fast_exp2(sc[e + 1]); ps2 += (f32x2_t){sc[e], sc[e + 1]}; }
;                 lrow += ps2.x + ps2.y;
;                 bf16x8 pb[2]; pb[0] = pack8(sc, 0); pb[1] = pack8(sc, 1);
; #pragma unroll
;                 for (int i = 0; i < NPV; ++i) {
;                     VWAIT(2 * ((NPV - 1 - i) < (DV - 1) ? (NPV - 1 - i) : (DV - 1)), vlo[i % DV], vhi[i % DV]);
;                     const bf16x8 vf = __builtin_shufflevector(vlo[i % DV], vhi[i % DV], 0, 1, 2, 3, 4, 5, 6, 7);
;                     o[i >> 1] = mfma32(vf, pb[i & 1], o[i >> 1]);
;                     if (i + DV < NPV) LDV(i + DV, hf);
;                 }
;                 __builtin_amdgcn_sched_barrier(0);
;                 if (hf == 0) {
; #pragma unroll
;                     for (int i = 0; i < DK; ++i) kf[i] = LDK(1, i);
;                     SGB(0x100, DK);
;                 }
;             }
	s_and_b64 vcc, exec, s[12:13]
	s_cbranch_vccnz .Lpc_skip5_i1
	v_lshl_add_u64 v[244:245], s[36:37], 0, v[154:155]
	v_lshl_add_u64 v[246:247], s[36:37], 0, v[166:167]
	v_cndmask_b32_e64 v245, v247, v245, s[22:23]
	v_cndmask_b32_e64 v244, v246, v244, s[22:23]
	s_add_i32 m0, s98, s83
	s_nop 0
	global_load_lds_dwordx4 v[244:245], off
.Lpc_skip5_i1:
	s_waitcnt lgkmcnt(10)
	v_mfma_f32_32x32x16_bf16 v[48:63], v[6:9], v[80:83], v[48:63]
	ds_read_b64_tr_b16 v[6:7], v173 offset:5312
	ds_read_b64_tr_b16 v[8:9], v173 offset:7872
	s_waitcnt lgkmcnt(10)
	v_mfma_f32_32x32x16_bf16 v[32:47], v[10:13], v[80:83], v[32:47]
	ds_read_b64_tr_b16 v[10:11], v173 offset:10240
	ds_read_b64_tr_b16 v[12:13], v173 offset:12800
	v_exp_f32_e32 v226, v226
	v_exp_f32_e32 v227, v227
	v_add_f32_e32 v172, v172, v226
	v_add_f32_e32 v196, v196, v227
	s_waitcnt lgkmcnt(10)
	v_mfma_f32_32x32x16_bf16 v[16:31], v[174:177], v[80:83], v[16:31]
	ds_read_b64_tr_b16 v[174:175], v173 offset:10304
	ds_read_b64_tr_b16 v[176:177], v173 offset:12864
	v_cvt_pk_bf16_f32 v226, v226, v227
	v_exp_f32_e32 v228, v228
	v_exp_f32_e32 v229, v229
	v_add_f32_e32 v172, v172, v228
	s_waitcnt lgkmcnt(10)
	v_mfma_f32_32x32x16_bf16 v[64:79], v[178:181], v[84:87], v[64:79]
	ds_read_b64_tr_b16 v[178:179], v173 offset:10368
	ds_read_b64_tr_b16 v[180:181], v173 offset:12928
	v_add_f32_e32 v196, v196, v229
	v_cvt_pk_bf16_f32 v227, v228, v229
	v_exp_f32_e32 v230, v230
	v_exp_f32_e32 v231, v231
	s_waitcnt lgkmcnt(10)
	v_mfma_f32_32x32x16_bf16 v[48:63], v[182:185], v[84:87], v[48:63]
	ds_read_b64_tr_b16 v[182:183], v173 offset:10432
	ds_read_b64_tr_b16 v[184:185], v173 offset:12992
	v_add_f32_e32 v172, v172, v230
	v_add_f32_e32 v196, v196, v231
	v_cvt_pk_bf16_f32 v228, v230, v231
	v_exp_f32_e32 v232, v232
	s_waitcnt lgkmcnt(10)
	v_mfma_f32_32x32x16_bf16 v[32:47], v[2:5], v[84:87], v[32:47]
	ds_read_b64_tr_b16 v[2:3], v173 offset:15360
	ds_read_b64_tr_b16 v[4:5], v173 offset:17920
	v_exp_f32_e32 v233, v233
	v_add_f32_e32 v172, v172, v232
	v_add_f32_e32 v196, v196, v233
	v_cvt_pk_bf16_f32 v229, v232, v233
	s_waitcnt lgkmcnt(10)
	v_mfma_f32_32x32x16_bf16 v[16:31], v[6:9], v[84:87], v[16:31]
	ds_read_b64_tr_b16 v[6:7], v173 offset:15424
	ds_read_b64_tr_b16 v[8:9], v173 offset:17984
	s_cmp_lg_u32 s99, 0
	s_cbranch_scc0 .Lpc_skip4_i1
	s_andn2_b64 vcc, exec, s[68:69]
	s_cbranch_vccnz .Lpc_skip4_i1
	v_lshl_add_u64 v[244:245], s[36:37], 0, v[156:157]
	v_lshl_add_u64 v[246:247], s[36:37], 0, v[168:169]
	v_cndmask_b32_e64 v245, v247, v245, s[24:25]
	v_cndmask_b32_e64 v244, v246, v244, s[24:25]
	s_add_i32 m0, s98, s46
	s_nop 0
	global_load_lds_dwordx4 v[244:245], off
.Lpc_skip4_i1:
	s_waitcnt lgkmcnt(10)
	v_mfma_f32_32x32x16_bf16 v[64:79], v[10:13], v[226:229], v[64:79]
	ds_read_b64_tr_b16 v[10:11], v173 offset:15488
	ds_read_b64_tr_b16 v[12:13], v173 offset:18048
	v_exp_f32_e32 v234, v234
	v_exp_f32_e32 v235, v235
	v_add_f32_e32 v172, v172, v234
	v_add_f32_e32 v196, v196, v235
	v_cvt_pk_bf16_f32 v230, v234, v235
	s_waitcnt lgkmcnt(10)
	v_mfma_f32_32x32x16_bf16 v[48:63], v[174:177], v[226:229], v[48:63]
	ds_read_b64_tr_b16 v[174:175], v173 offset:15552
	ds_read_b64_tr_b16 v[176:177], v173 offset:18112
	v_exp_f32_e32 v236, v236
	v_exp_f32_e32 v237, v237
	v_add_f32_e32 v172, v172, v236
	v_add_f32_e32 v196, v196, v237
	v_cvt_pk_bf16_f32 v231, v236, v237
	s_waitcnt lgkmcnt(10)
	v_mfma_f32_32x32x16_bf16 v[32:47], v[178:181], v[226:229], v[32:47]
	v_exp_f32_e32 v238, v238
	v_exp_f32_e32 v239, v239
	v_add_f32_e32 v172, v172, v238
	v_add_f32_e32 v196, v196, v239
	v_cvt_pk_bf16_f32 v232, v238, v239
	s_waitcnt lgkmcnt(8)
	v_mfma_f32_32x32x16_bf16 v[16:31], v[182:185], v[226:229], v[16:31]
	v_exp_f32_e32 v240, v240
	v_exp_f32_e32 v241, v241
	v_add_f32_e32 v172, v172, v240
	v_add_f32_e32 v196, v196, v241
	v_cvt_pk_bf16_f32 v233, v240, v241
	s_waitcnt lgkmcnt(6)
	s_nop 0
	v_mfma_f32_32x32x16_bf16 v[64:79], v[2:5], v[230:233], v[64:79]
	s_waitcnt lgkmcnt(4)
	v_mfma_f32_32x32x16_bf16 v[48:63], v[6:9], v[230:233], v[48:63]
	s_waitcnt lgkmcnt(2)
	v_mfma_f32_32x32x16_bf16 v[32:47], v[10:13], v[230:233], v[32:47]
	s_waitcnt lgkmcnt(0)
	v_mfma_f32_32x32x16_bf16 v[16:31], v[174:177], v[230:233], v[16:31]
	v_add_f32_e32 v172, v172, v196
	s_cmp_ge_u32 s84, s31
	s_mov_b64 s[80:81], -1
	s_cbranch_scc0 .LBB0_1388

; __global__ void __launch_bounds__(512, 2) fwd_kernel(Args a_unused) {
	.amdhsa_kernel _Z10fwd_kernel4Args
		.amdhsa_group_segment_fixed_size 0
		.amdhsa_private_segment_fixed_size 0
		.amdhsa_kernarg_size 440
		.amdhsa_user_sgpr_count 2
		.amdhsa_user_sgpr_dispatch_ptr 0
		.amdhsa_user_sgpr_queue_ptr 0
		.amdhsa_user_sgpr_kernarg_segment_ptr 1
		.amdhsa_user_sgpr_dispatch_id 0
		.amdhsa_user_sgpr_kernarg_preload_length 0
		.amdhsa_user_sgpr_kernarg_preload_offset 0
		.amdhsa_user_sgpr_private_segment_size 0
		.amdhsa_uses_dynamic_stack 0
		.amdhsa_enable_private_segment 0
		.amdhsa_system_sgpr_workgroup_id_x 1
		.amdhsa_system_sgpr_workgroup_id_y 0
		.amdhsa_system_sgpr_workgroup_id_z 0
		.amdhsa_system_sgpr_workgroup_info 0
		.amdhsa_system_vgpr_workitem_id 2
		.amdhsa_next_free_vgpr 256
		.amdhsa_next_free_sgpr 102
		.amdhsa_accum_offset 256
		.amdhsa_reserve_vcc 1
		.amdhsa_float_round_mode_32 0
		.amdhsa_float_round_mode_16_64 0
		.amdhsa_float_denorm_mode_32 3
		.amdhsa_float_denorm_mode_16_64 3
		.amdhsa_dx10_clamp 1
		.amdhsa_ieee_mode 1
		.amdhsa_fp16_overflow 0
		.amdhsa_tg_split 0
		.amdhsa_exception_fp_ieee_invalid_op 0
		.amdhsa_exception_fp_denorm_src 0
		.amdhsa_exception_fp_ieee_div_zero 0
		.amdhsa_exception_fp_ieee_overflow 0
		.amdhsa_exception_fp_ieee_underflow 0
		.amdhsa_exception_fp_ieee_inexact 0
		.amdhsa_exception_int_div_zero 0
	.end_amdhsa_kernel

; __global__ void __launch_bounds__(512, 2) fwd_kernel(Args a_unused) {
amdhsa.kernels:
  - .agpr_count:     0
    .args:
      - .offset:         0
        .size:           184
        .value_kind:     by_value
      - .offset:         184
        .size:           4
        .value_kind:     hidden_block_count_x
      - .offset:         188
        .size:           4
        .value_kind:     hidden_block_count_y
      - .offset:         192
        .size:           4
        .value_kind:     hidden_block_count_z
      - .offset:         196
        .size:           2
        .value_kind:     hidden_group_size_x
      - .offset:         198
        .size:           2
        .value_kind:     hidden_group_size_y
      - .offset:         200
        .size:           2
        .value_kind:     hidden_group_size_z
      - .offset:         202
        .size:           2
        .value_kind:     hidden_remainder_x
      - .offset:         204
        .size:           2
        .value_kind:     hidden_remainder_y
      - .offset:         206
        .size:           2
        .value_kind:     hidden_remainder_z
      - .offset:         224
        .size:           8
        .value_kind:     hidden_global_offset_x
      - .offset:         232
        .size:           8
        .value_kind:     hidden_global_offset_y
      - .offset:         240
        .size:           8
        .value_kind:     hidden_global_offset_z
      - .offset:         248
        .size:           2
        .value_kind:     hidden_grid_dims
      - .offset:         272
        .size:           8
        .value_kind:     hidden_multigrid_sync_arg
      - .offset:         304
        .size:           4
        .value_kind:     hidden_dynamic_lds_size
    .group_segment_fixed_size: 0
    .kernarg_segment_align: 8
    .kernarg_segment_size: 440
    .language:       OpenCL C
    .language_version:
      - 2
      - 0
    .max_flat_workgroup_size: 512
    .name:           _Z10fwd_kernel4Args
    .private_segment_fixed_size: 0
    .sgpr_count:     108
    .sgpr_spill_count: 26
    .symbol:         _Z10fwd_kernel4Args.kd
    .uniform_work_group_size: 1
    .uses_dynamic_stack: false
    .vgpr_count:     256
    .vgpr_spill_count: 0
    .wavefront_size: 64
